# phase header: workspace-pointer scalar load also issued before the first wait (via a temporary SGPR pair)
# speedup vs baseline: 1.0028x; 1.0002x over previous
; __device__ __forceinline__ float bf2f(bf16_t v) { return __uint_as_float(((unsigned)v) << 16); }
; template <int MODE>
; __device__ __forceinline__ void sample_gemm(const Params& p, int l, const int tid) {
;     const int wid = tid >> 6, lane = tid & 63, r16 = lane & 15, quad = lane >> 4;
;     const bf16_t* A = (const bf16_t*)(p.ws + (MODE == 2 ? WS_H : WS_MERGED)) + (size_t)MP * 2048;
;     const bf16_t* Bt = (const bf16_t*)(p.ws + (MODE == 2 ? WS_WP : WS_WO));
;     for (int sl = blockIdx.x; sl < 128; sl += gridDim.x) {
;         const int n0 = sl * 16;
;         const bf16_t* a0 = A + (size_t)(wid * 32 + r16) * 2048 + quad * 8; const bf16_t* a1 = a0 + 16 * 2048; const bf16_t* bp = Bt + (size_t)(n0 + r16) * 2048 + quad * 8;
;         f32x4 c[2][2];
; #pragma unroll
;         for (int i = 0; i < 2; ++i)
; #pragma unroll
;             for (int j = 0; j < 2; ++j) c[i][j] = (f32x4){0.f, 0.f, 0.f, 0.f};
; #pragma unroll
;         for (int hh = 0; hh < 2; ++hh) {
; #pragma unroll 8
;             for (int k = hh * 1024; k < hh * 1024 + 1024; k += 32) {
;                 const bf16x8 fa0 = *(const bf16x8*)(a0 + k), fa1 = *(const bf16x8*)(a1 + k), fb = *(const bf16x8*)(bp + k);
;                 const int ci = (MODE == 2) ? hh : 0;
;                 c[ci][0] = __builtin_amdgcn_mfma_f32_16x16x32_bf16(fa0, fb, c[ci][0], 0, 0, 0);
;                 c[ci][1] = __builtin_amdgcn_mfma_f32_16x16x32_bf16(fa1, fb, c[ci][1], 0, 0, 0);
;             }
;         }
;         const int col = n0 + r16;
; #pragma unroll
;         for (int i = 0; i < 2; ++i)
; #pragma unroll
;             for (int j = 0; j < 4; ++j) {
;                 const int row = MP + wid * 32 + i * 16 + quad * 4 + j;
;                 if (MODE == 2) {
;                     const float sa = bf2f(((const bf16_t*)(p.ws + WS_MA))[(size_t)row * 2048 + col]), sb = bf2f(((const bf16_t*)(p.ws + WS_MB))[(size_t)row * 2048 + col]);
; __global__ void __launch_bounds__(512, 2) mega(Params p) {
;     ...
;         int z = 0; asm volatile("" : "+s"(z));
;         asm volatile("" : "+s"(pp));
;         Params q;
; #pragma unroll
;         for (int i = 0; i < 22; ++i) q.in[i] = pp->in[i];
;         q.out = pp->out; q.ws = pp->ws; q.ph_lo = 0; q.ph_hi = 0;
;         const int tid = (int)threadIdx.x + z;
;         const int l = ph / NPH, s = ph % NPH;
.LBB0_10:
	v_readlane_b32 s20, v248, 4
	s_mov_b32 s2, s79
	v_readlane_b32 s21, v248, 5
	s_load_dwordx16 s[4:19], s[20:21], 0x0
	s_load_dwordx2 s[98:99], s[20:21], 0xb8
	v_writelane_b32 v246, s80, 27
	v_add_u32_e32 v188, s2, v204
	s_mov_b32 s1, s79
	v_writelane_b32 v246, s81, 28
	v_writelane_b32 v246, s82, 29
	v_writelane_b32 v246, s83, 30
	s_load_dwordx16 s[76:91], s[20:21], 0x78
	s_waitcnt lgkmcnt(0)
	v_writelane_b32 v246, s4, 31
	v_writelane_b32 v248, s20, 4
	v_writelane_b32 v246, s5, 32
	v_writelane_b32 v246, s6, 33
	v_writelane_b32 v246, s7, 34
	v_writelane_b32 v246, s8, 35
	v_writelane_b32 v246, s9, 36
	v_writelane_b32 v246, s10, 37
	v_writelane_b32 v246, s11, 38
	v_writelane_b32 v246, s12, 39
	v_writelane_b32 v246, s13, 40
	v_writelane_b32 v246, s14, 41
	v_writelane_b32 v246, s15, 42
	v_writelane_b32 v246, s16, 43
	v_writelane_b32 v246, s17, 44
	v_writelane_b32 v246, s18, 45
	v_writelane_b32 v246, s19, 46
	s_mov_b64 s[8:9], s[98:99]
	v_readlane_b32 s4, v246, 27
	v_readlane_b32 s6, v246, 29
	s_mul_hi_i32 s2, s6, 0x2aaaaaab
	s_lshr_b32 s3, s2, 31
	s_ashr_i32 s2, s2, 1
	s_add_i32 s4, s2, s3
	s_mov_b32 s2, s4
	v_readlane_b32 s5, v246, 28
	v_readlane_b32 s7, v246, 30
	v_writelane_b32 v246, s2, 47
	s_movk_i32 s0, 0x1800
	v_writelane_b32 v248, s21, 5
	v_writelane_b32 v246, s3, 48
	s_mul_i32 s2, s4, 12
	s_sub_i32 s4, s6, s2
	v_writelane_b32 v246, s4, 49
	s_cmp_lt_i32 s4, 5
	s_mov_b64 s[4:5], 0
	v_writelane_b32 v246, s4, 50
	s_mov_b64 s[2:3], -1
	s_nop 0
	v_writelane_b32 v246, s5, 51
	s_waitcnt lgkmcnt(0)
	v_writelane_b32 v246, s8, 52
	s_nop 1
	v_writelane_b32 v246, s9, 53
	s_cbranch_scc1 .LBB0_351
	v_readlane_b32 s4, v246, 49
	s_cmp_gt_i32 s4, 7
	s_mov_b64 s[4:5], 0
	v_writelane_b32 v246, s4, 50
	s_mov_b64 s[16:17], 0
	s_nop 0
	v_writelane_b32 v246, s5, 51
	s_mov_b64 s[4:5], 0
	s_cbranch_scc0 .LBB0_102
	v_readlane_b32 s6, v246, 49
	s_cmp_gt_i32 s6, 8
	s_mov_b64 s[6:7], 0
	s_mov_b64 s[4:5], -1
	s_mov_b64 s[2:3], 0
	v_writelane_b32 v246, s6, 50
	s_nop 1
	v_writelane_b32 v246, s7, 51
	s_cbranch_scc0 .LBB0_102
	v_readlane_b32 s4, v246, 49
	s_cmp_gt_i32 s4, 9
	s_cbranch_scc0 .LBB0_89
	s_cmp_eq_u32 s4, 10
	s_mov_b64 s[4:5], -1
	v_writelane_b32 v246, s4, 50
	s_nop 1
	v_writelane_b32 v246, s5, 51
	s_cbranch_scc0 .LBB0_90
	v_readlane_b32 s4, v248, 8
	v_readlane_b32 s5, v248, 9
	s_andn2_b64 vcc, exec, s[4:5]
	s_waitcnt vmcnt(0)
	v_and_b32_e32 v44, 15, v188
	s_cbranch_vccnz .LBB0_22
	v_ashrrev_i32_e32 v0, 1, v188
	v_bfe_u32 v4, v188, 4, 2
	v_and_b32_e32 v5, 0xffffffe0, v0
	v_lshl_or_b32 v6, v4, 2, v5
	v_add_u32_e32 v0, 0x8000, v6
	v_ashrrev_i32_e32 v1, 31, v0
	v_lshlrev_b64 v[18:19], 11, v[0:1]
	v_add_u32_e32 v0, 0x8001, v6
	v_ashrrev_i32_e32 v1, 31, v0
	v_lshlrev_b64 v[20:21], 11, v[0:1]
	v_add_u32_e32 v0, 0x8002, v6
	v_ashrrev_i32_e32 v1, 31, v0
	v_readlane_b32 s4, v248, 4
	v_lshlrev_b64 v[22:23], 11, v[0:1]
	v_add_u32_e32 v0, 0x8003, v6
	v_readlane_b32 s5, v248, 5
	v_ashrrev_i32_e32 v1, 31, v0
	s_load_dwordx2 s[10:11], s[4:5], 0xb8
	v_lshlrev_b64 v[24:25], 11, v[0:1]
	v_add_u32_e32 v0, 0x8011, v6
	v_ashrrev_i32_e32 v1, 31, v0
	v_lshlrev_b64 v[26:27], 11, v[0:1]
	v_add_u32_e32 v0, 0x8012, v6
	v_ashrrev_i32_e32 v1, 31, v0
	v_lshlrev_b64 v[28:29], 11, v[0:1]
	v_add_u32_e32 v0, 0x8013, v6
	s_waitcnt lgkmcnt(0)
	s_add_u32 s4, s10, 0x2c600000
	v_ashrrev_i32_e32 v1, 31, v0
	s_addc_u32 s5, s11, 0
	v_lshlrev_b64 v[30:31], 11, v[0:1]
	v_or_b32_e32 v0, v5, v44
	s_add_u32 s6, s10, 0x34700000
	v_ashrrev_i32_e32 v1, 31, v0
	s_addc_u32 s7, s11, 0
	v_add_u32_e32 v2, 0x8010, v6
	v_lshlrev_b64 v[0:1], 12, v[0:1]
	s_add_u32 s8, s10, 0xc200000
	v_ashrrev_i32_e32 v3, 31, v2
	v_lshl_add_u64 v[32:33], s[10:11], 0, v[0:1]
	v_readlane_b32 s10, v247, 29
	s_addc_u32 s9, s11, 0
	v_lshlrev_b64 v[16:17], 11, v[2:3]
	v_lshlrev_b32_e32 v136, 4, v4
	v_add_u32_e32 v34, s10, v44
	v_readlane_b32 s10, v247, 56
